# combine phases: lanes touch the cache lines of their expert-output rows at the top of each 4-token batch (gathers then hit L2)
# baseline (speedup 1.0000x reference)
.LBB0_1091:
	s_ashr_i32 s41, s40, 31
	s_lshl_b64 s[42:43], s[40:41], 11
	v_lshl_add_u64 v[124:125], v[100:101], 0, s[42:43]
	global_load_dwordx4 v[76:79], v[124:125], off
	global_load_dwordx4 v[72:75], v[124:125], off offset:1024
	global_load_dwordx4 v[68:71], v[124:125], off offset:2048
	global_load_dwordx4 v[64:67], v[124:125], off offset:3072
	s_lshl_b64 s[14:15], s[40:41], 6
	s_waitcnt lgkmcnt(0)
	v_lshl_add_u64 v[48:49], s[40:41], 2, v[92:93]
	v_lshl_add_u64 v[50:51], v[90:91], 0, s[14:15]
	v_add_co_u32_e32 v104, vcc, 0x1000, v124
	s_nop 1
	v_addc_co_u32_e32 v105, vcc, 0, v125, vcc
	global_load_dword v168, v[48:49], off
	global_load_dword v169, v[50:51], off
	global_load_dwordx4 v[60:63], v[104:105], off
	global_load_dwordx4 v[56:59], v[104:105], off offset:1024
	global_load_dwordx4 v[52:55], v[104:105], off offset:2048
	s_nop 0
	global_load_dwordx4 v[48:51], v[104:105], off offset:3072
	s_waitcnt vmcnt(5)
	v_cmp_lt_i32_e64 s[98:99], -1, v168
	s_and_saveexec_b64 s[100:101], s[98:99]
	v_ashrrev_i32_e32 v201, 31, v168
	v_mov_b32_e32 v200, v168
	v_lshlrev_b64 v[200:201], 10, v[200:201]
	v_lshl_add_u64 v[200:201], v[88:89], 0, v[200:201]
	global_load_dword v202, v[200:201], off
	global_load_dword v202, v[200:201], off offset:128
	global_load_dword v202, v[200:201], off offset:256
	global_load_dword v202, v[200:201], off offset:384
	global_load_dword v202, v[200:201], off offset:512
	global_load_dword v202, v[200:201], off offset:640
	global_load_dword v202, v[200:201], off offset:768
	global_load_dword v202, v[200:201], off offset:896
	s_mov_b64 exec, s[100:101]
	s_waitcnt vmcnt(5)
	v_cmp_lt_i32_e64 s[14:15], -1, v168
	s_and_b32 s52, s14, 0xffff
	s_cmp_eq_u32 s52, 0
	s_cbranch_scc1 .LBB0_1096
	v_mov_b32_e32 v112, 0
	v_mov_b32_e32 v113, v112
	v_mov_b32_e32 v104, v112
	v_mov_b32_e32 v105, v112
	v_mov_b32_e32 v108, v112
	v_mov_b32_e32 v109, v112
	v_mov_b32_e32 v110, v112
	v_mov_b32_e32 v111, v112
	v_mov_b32_e32 v114, v112
	v_mov_b32_e32 v115, v112
	v_mov_b32_e32 v106, v112
	v_mov_b32_e32 v107, v112
	v_mov_b32_e32 v118, v112
	v_mov_b32_e32 v119, v112
	v_mov_b32_e32 v116, v112
	v_mov_b32_e32 v117, v112
	s_branch .LBB0_1094

.LBB0_2005:
	s_ashr_i32 s3, s2, 31
	s_lshl_b64 s[0:1], s[2:3], 6
	v_lshl_add_u64 v[18:19], v[52:53], 0, s[0:1]
	s_lshl_b64 s[0:1], s[2:3], 11
	v_lshl_add_u64 v[58:59], v[56:57], 0, s[0:1]
	v_lshl_add_u64 v[16:17], s[2:3], 2, v[50:51]
	v_add_co_u32_e32 v60, vcc, 0x1000, v58
	global_load_dword v89, v[16:17], off
	global_load_dword v90, v[18:19], off
	global_load_dwordx4 v[44:47], v[58:59], off
	global_load_dwordx4 v[40:43], v[58:59], off offset:1024
	global_load_dwordx4 v[36:39], v[58:59], off offset:2048
	v_addc_co_u32_e32 v61, vcc, 0, v59, vcc
	global_load_dwordx4 v[32:35], v[58:59], off offset:3072
	global_load_dwordx4 v[28:31], v[60:61], off
	global_load_dwordx4 v[24:27], v[60:61], off offset:1024
	global_load_dwordx4 v[20:23], v[60:61], off offset:2048
	global_load_dwordx4 v[16:19], v[60:61], off offset:3072
	s_waitcnt vmcnt(9)
	v_cmp_lt_i32_e64 s[98:99], -1, v89
	s_and_saveexec_b64 s[100:101], s[98:99]
	v_ashrrev_i32_e32 v123, 31, v89
	v_mov_b32_e32 v122, v89
	v_lshlrev_b64 v[122:123], 10, v[122:123]
	v_lshl_add_u64 v[122:123], v[54:55], 0, v[122:123]
	global_load_dword v124, v[122:123], off
	global_load_dword v124, v[122:123], off offset:128
	global_load_dword v124, v[122:123], off offset:256
	global_load_dword v124, v[122:123], off offset:384
	global_load_dword v124, v[122:123], off offset:512
	global_load_dword v124, v[122:123], off offset:640
	global_load_dword v124, v[122:123], off offset:768
	global_load_dword v124, v[122:123], off offset:896
	s_mov_b64 exec, s[100:101]
	s_waitcnt vmcnt(0)
	v_cmp_lt_i32_e64 s[0:1], -1, v89
	s_and_b32 s11, s0, 0xffff
	s_cmp_eq_u32 s11, 0
	s_cbranch_scc1 .LBB0_2010
	v_mov_b32_e32 v64, 0
	v_mov_b32_e32 v65, v64
	v_mov_b32_e32 v58, v64
	v_mov_b32_e32 v59, v64
	v_mov_b32_e32 v60, v64
	v_mov_b32_e32 v61, v64
	v_mov_b32_e32 v62, v64
	v_mov_b32_e32 v63, v64
	v_mov_b32_e32 v68, v64
	v_mov_b32_e32 v69, v64
	v_mov_b32_e32 v66, v64
	v_mov_b32_e32 v67, v64
	v_mov_b32_e32 v72, v64
	v_mov_b32_e32 v73, v64
	v_mov_b32_e32 v70, v64
	v_mov_b32_e32 v71, v64
	s_branch .LBB0_2008
